# in-projection: the 32 workgroups that have one unit less and no S5 tables start half a unit late (phase offset against the rest of the chip)
# baseline (speedup 1.0000x reference)
.LBB0_102:
	v_readlane_b32 s2, v251, 0
	s_nop 3
	s_sub_u32 s2, s2, 160
	s_cmp_lt_u32 s2, 32
	s_cbranch_scc0 .Lph_skip
	s_sleep 127
	s_sleep 127
	s_sleep 127
	s_sleep 127
